# rw_lora: the three f32-MFMA LoRA matmuls run as one 48-step operand stream (next matmul's operands prefetched during the current one's tail, C=0 first step)
# speedup vs baseline: 1.0058x; 1.0058x over previous
.LBB0_944:
	s_lshl_b32 s18, s48, 4
	s_mov_b32 s10, 0xffffde00
	s_mov_b32 s11, -1
	s_mov_b32 s20, 0x2200
	s_mov_b32 s21, 0
	global_load_dword v50, v[2:3], off
	global_load_dword v51, v[4:5], off
	global_load_dword v52, v[6:7], off
	global_load_dword v53, v[8:9], off
	v_or_b32_e32 v20, s18, v220
	v_mad_i64_i32 v[22:23], s[0:1], v20, s23, v[14:15]
	v_lshl_add_u64 v[22:23], v[22:23], 0, s[16:17]
	v_lshl_add_u64 v[26:27], v[22:23], 0, v[0:1]
	v_lshl_add_u64 v[34:35], v[26:27], 0, s[10:11]
	v_lshl_add_u64 v[36:37], v[26:27], 0, s[20:21]
	global_load_ushort v38, v[26:27], off
	global_load_ushort v42, v[34:35], off
	global_load_ushort v46, v[36:37], off
	v_lshl_add_u64 v[28:29], v[22:23], 0, v[18:19]
	v_lshl_add_u64 v[34:35], v[28:29], 0, s[10:11]
	v_lshl_add_u64 v[36:37], v[28:29], 0, s[20:21]
	global_load_ushort v39, v[28:29], off
	global_load_ushort v43, v[34:35], off
	global_load_ushort v47, v[36:37], off
	v_or_b32_e32 v21, s18, v69
	v_mad_i64_i32 v[24:25], s[0:1], v21, s23, v[14:15]
	v_lshl_add_u64 v[24:25], v[24:25], 0, s[16:17]
	v_lshl_add_u64 v[30:31], v[24:25], 0, v[0:1]
	v_lshl_add_u64 v[34:35], v[30:31], 0, s[10:11]
	v_lshl_add_u64 v[36:37], v[30:31], 0, s[20:21]
	global_load_ushort v40, v[30:31], off
	global_load_ushort v44, v[34:35], off
	global_load_ushort v48, v[36:37], off
	v_lshl_add_u64 v[32:33], v[24:25], 0, v[18:19]
	v_lshl_add_u64 v[34:35], v[32:33], 0, s[10:11]
	v_lshl_add_u64 v[36:37], v[32:33], 0, s[20:21]
	global_load_ushort v41, v[32:33], off
	global_load_ushort v45, v[34:35], off
	global_load_ushort v49, v[36:37], off
	s_waitcnt vmcnt(0)
	v_and_b32_e32 v54, v71, v20
	v_lshlrev_b32_e32 v55, 16, v38
	v_lshlrev_b32_e32 v56, 16, v42
	v_lshlrev_b32_e32 v57, 16, v46
	v_cmp_ne_u32_e32 vcc, 0, v54
	s_nop 1
	v_cndmask_b32_e32 v56, 0, v56, vcc
	v_cmp_ne_u32_e32 vcc, s22, v54
	s_nop 1
	v_cndmask_b32_e32 v57, 0, v57, vcc
	v_sub_f32_e32 v56, v56, v55
	v_sub_f32_e32 v57, v57, v55
	v_mul_f32_e32 v56, v56, v50
	v_mul_f32_e32 v57, v57, v51
	v_add_f32_e32 v56, v56, v55
	v_add_f32_e32 v56, v56, v57
	v_add_f32_e64 v57, |v56|, |v56|
	v_mul_f32_e32 v58, 0x3fb8aa3b, v57
	v_rndne_f32_e32 v59, v58
	v_sub_f32_e32 v60, v58, v59
	v_fma_f32 v58, v57, s35, -v58
	v_fmac_f32_e32 v58, 0x32a5705f, v57
	v_add_f32_e32 v58, v60, v58
	v_cvt_i32_f32_e32 v59, v59
	v_exp_f32_e32 v58, v58
	v_cmp_ngt_f32_e32 vcc, s44, v57
	v_ldexp_f32 v58, v58, v59
	s_nop 0
	v_cndmask_b32_e32 v58, 0, v58, vcc
	v_cmp_nlt_f32_e32 vcc, s45, v57
	s_nop 1
	v_cndmask_b32_e32 v57, v73, v58, vcc
	v_add_f32_e32 v57, 1.0, v57
	v_rcp_f32_e32 v57, v57
	s_nop 0
	v_fma_f32 v58, v57, -2.0, 1.0
	v_mul_f32_e32 v57, v56, v56
	v_fmamk_f32 v59, v57, 0xbbbac73d, v72
	v_fmaak_f32 v59, v57, v59, 0xbd5c1c4e
	v_fmaak_f32 v59, v57, v59, 0x3e088382
	v_fmaak_f32 v59, v57, v59, 0xbeaaaa99
	v_mul_f32_e64 v59, |v56|, v59
	v_fma_f32 v59, v57, v59, |v56|
	v_cmp_nlt_f32_e64 vcc, |v56|, s34
	s_nop 1
	v_cndmask_b32_e32 v58, v59, v58, vcc
	v_bfi_b32 v56, s46, v58, v56
	ds_write_b32 v68, v56
	v_and_b32_e32 v54, v71, v20
	v_lshlrev_b32_e32 v55, 16, v39
	v_lshlrev_b32_e32 v56, 16, v43
	v_lshlrev_b32_e32 v57, 16, v47
	v_cmp_ne_u32_e32 vcc, 0, v54
	s_nop 1
	v_cndmask_b32_e32 v56, 0, v56, vcc
	v_cmp_ne_u32_e32 vcc, s22, v54
	s_nop 1
	v_cndmask_b32_e32 v57, 0, v57, vcc
	v_sub_f32_e32 v56, v56, v55
	v_sub_f32_e32 v57, v57, v55
	v_mul_f32_e32 v56, v56, v52
	v_mul_f32_e32 v57, v57, v53
	v_add_f32_e32 v56, v56, v55
	v_add_f32_e32 v56, v56, v57
	ds_write_b32 v68, v56 offset:4096
	v_and_b32_e32 v54, v71, v21
	v_lshlrev_b32_e32 v55, 16, v40
	v_lshlrev_b32_e32 v56, 16, v44
	v_lshlrev_b32_e32 v57, 16, v48
	v_cmp_ne_u32_e32 vcc, 0, v54
	s_nop 1
	v_cndmask_b32_e32 v56, 0, v56, vcc
	v_cmp_ne_u32_e32 vcc, s22, v54
	s_nop 1
	v_cndmask_b32_e32 v57, 0, v57, vcc
	v_sub_f32_e32 v56, v56, v55
	v_sub_f32_e32 v57, v57, v55
	v_mul_f32_e32 v56, v56, v50
	v_mul_f32_e32 v57, v57, v51
	v_add_f32_e32 v56, v56, v55
	v_add_f32_e32 v56, v56, v57
	v_add_f32_e64 v57, |v56|, |v56|
	v_mul_f32_e32 v58, 0x3fb8aa3b, v57
	v_rndne_f32_e32 v59, v58
	v_sub_f32_e32 v60, v58, v59
	v_fma_f32 v58, v57, s35, -v58
	v_fmac_f32_e32 v58, 0x32a5705f, v57
	v_add_f32_e32 v58, v60, v58
	v_cvt_i32_f32_e32 v59, v59
	v_exp_f32_e32 v58, v58
	v_cmp_ngt_f32_e32 vcc, s44, v57
	v_ldexp_f32 v58, v58, v59
	s_nop 0
	v_cndmask_b32_e32 v58, 0, v58, vcc
	v_cmp_nlt_f32_e32 vcc, s45, v57
	s_nop 1
	v_cndmask_b32_e32 v57, v73, v58, vcc
	v_add_f32_e32 v57, 1.0, v57
	v_rcp_f32_e32 v57, v57
	s_nop 0
	v_fma_f32 v58, v57, -2.0, 1.0
	v_mul_f32_e32 v57, v56, v56
	v_fmamk_f32 v59, v57, 0xbbbac73d, v72
	v_fmaak_f32 v59, v57, v59, 0xbd5c1c4e
	v_fmaak_f32 v59, v57, v59, 0x3e088382
	v_fmaak_f32 v59, v57, v59, 0xbeaaaa99
	v_mul_f32_e64 v59, |v56|, v59
	v_fma_f32 v59, v57, v59, |v56|
	v_cmp_nlt_f32_e64 vcc, |v56|, s34
	s_nop 1
	v_cndmask_b32_e32 v58, v59, v58, vcc
	v_bfi_b32 v56, s46, v58, v56
	ds_write_b32 v70, v56
	v_and_b32_e32 v54, v71, v21
	v_lshlrev_b32_e32 v55, 16, v41
	v_lshlrev_b32_e32 v56, 16, v45
	v_lshlrev_b32_e32 v57, 16, v49
	v_cmp_ne_u32_e32 vcc, 0, v54
	s_nop 1
	v_cndmask_b32_e32 v56, 0, v56, vcc
	v_cmp_ne_u32_e32 vcc, s22, v54
	s_nop 1
	v_cndmask_b32_e32 v57, 0, v57, vcc
	v_sub_f32_e32 v56, v56, v55
	v_sub_f32_e32 v57, v57, v55
	v_mul_f32_e32 v56, v56, v52
	v_mul_f32_e32 v57, v57, v53
	v_add_f32_e32 v56, v56, v55
	v_add_f32_e32 v56, v56, v57
	ds_write_b32 v70, v56 offset:4096
	s_waitcnt lgkmcnt(0)
	s_barrier
	v_and_b32_e32 v112, 63, v164
	v_lshrrev_b32_e32 v113, 6, v164
	v_lshlrev_b32_e32 v107, 2, v112
	v_lshrrev_b32_e32 v114, 4, v112
	v_and_b32_e32 v115, 15, v112
	v_lshlrev_b32_e32 v111, 11, v114
	v_lshl_add_u32 v111, v113, 8, v111
	v_lshl_add_u32 v111, v115, 4, v111
	v_mul_u32_u24_e32 v110, 0x3000, v113
	v_add_u32_e32 v110, 0x2000, v110
	v_lshl_add_u32 v109, v114, 10, v110
	v_lshl_add_u32 v109, v115, 4, v109
	v_lshl_add_u32 v110, v112, 2, v110
	v_readlane_b32 s50, v255, 27
	v_readlane_b32 s51, v255, 28
	v_readlane_b32 s54, v255, 31
	v_readlane_b32 s55, v255, 32
	s_add_u32 s52, s50, 0x20000
	s_addc_u32 s53, s51, 0
	v_mov_b32_e32 v108, v111
	global_load_dwordx4 v[92:95], v108, s[50:51]
	v_add_u32_e32 v108, 0x2000, v108
	ds_read_b32 v104, v107 offset:0
	global_load_dwordx4 v[96:99], v108, s[50:51]
	v_add_u32_e32 v108, 0x2000, v108
	ds_read_b32 v105, v107 offset:256
	global_load_dwordx4 v[100:103], v108, s[50:51]
	v_add_u32_e32 v108, 0x2000, v108
	ds_read_b32 v106, v107 offset:512
	s_waitcnt vmcnt(2) lgkmcnt(2)
	v_mfma_f32_16x16x4_f32 v[76:79], v104, v92, 0
	v_mfma_f32_16x16x4_f32 v[80:83], v104, v93, 0
	v_mfma_f32_16x16x4_f32 v[84:87], v104, v94, 0
	v_mfma_f32_16x16x4_f32 v[88:91], v104, v95, 0
	global_load_dwordx4 v[92:95], v108, s[50:51]
	v_add_u32_e32 v108, 0x2000, v108
	ds_read_b32 v104, v107 offset:768
	s_waitcnt vmcnt(2) lgkmcnt(2)
	v_mfma_f32_16x16x4_f32 v[76:79], v105, v96, v[76:79]
	v_mfma_f32_16x16x4_f32 v[80:83], v105, v97, v[80:83]
	v_mfma_f32_16x16x4_f32 v[84:87], v105, v98, v[84:87]
	v_mfma_f32_16x16x4_f32 v[88:91], v105, v99, v[88:91]
	global_load_dwordx4 v[96:99], v108, s[50:51]
	v_add_u32_e32 v108, 0x2000, v108
	ds_read_b32 v105, v107 offset:1024
	s_waitcnt vmcnt(2) lgkmcnt(2)
	v_mfma_f32_16x16x4_f32 v[76:79], v106, v100, v[76:79]
	v_mfma_f32_16x16x4_f32 v[80:83], v106, v101, v[80:83]
	v_mfma_f32_16x16x4_f32 v[84:87], v106, v102, v[84:87]
	v_mfma_f32_16x16x4_f32 v[88:91], v106, v103, v[88:91]
	global_load_dwordx4 v[100:103], v108, s[50:51]
	v_add_u32_e32 v108, 0x2000, v108
	ds_read_b32 v106, v107 offset:1280
	s_waitcnt vmcnt(2) lgkmcnt(2)
	v_mfma_f32_16x16x4_f32 v[76:79], v104, v92, v[76:79]
	v_mfma_f32_16x16x4_f32 v[80:83], v104, v93, v[80:83]
	v_mfma_f32_16x16x4_f32 v[84:87], v104, v94, v[84:87]
	v_mfma_f32_16x16x4_f32 v[88:91], v104, v95, v[88:91]
	global_load_dwordx4 v[92:95], v108, s[50:51]
	v_add_u32_e32 v108, 0x2000, v108
	ds_read_b32 v104, v107 offset:1536
	s_waitcnt vmcnt(2) lgkmcnt(2)
	v_mfma_f32_16x16x4_f32 v[76:79], v105, v96, v[76:79]
	v_mfma_f32_16x16x4_f32 v[80:83], v105, v97, v[80:83]
	v_mfma_f32_16x16x4_f32 v[84:87], v105, v98, v[84:87]
	v_mfma_f32_16x16x4_f32 v[88:91], v105, v99, v[88:91]
	global_load_dwordx4 v[96:99], v108, s[50:51]
	v_add_u32_e32 v108, 0x2000, v108
	ds_read_b32 v105, v107 offset:1792
	s_waitcnt vmcnt(2) lgkmcnt(2)
	v_mfma_f32_16x16x4_f32 v[76:79], v106, v100, v[76:79]
	v_mfma_f32_16x16x4_f32 v[80:83], v106, v101, v[80:83]
	v_mfma_f32_16x16x4_f32 v[84:87], v106, v102, v[84:87]
	v_mfma_f32_16x16x4_f32 v[88:91], v106, v103, v[88:91]
	global_load_dwordx4 v[100:103], v108, s[50:51]
	v_add_u32_e32 v108, 0x2000, v108
	ds_read_b32 v106, v107 offset:2048
	s_waitcnt vmcnt(2) lgkmcnt(2)
	v_mfma_f32_16x16x4_f32 v[76:79], v104, v92, v[76:79]
	v_mfma_f32_16x16x4_f32 v[80:83], v104, v93, v[80:83]
	v_mfma_f32_16x16x4_f32 v[84:87], v104, v94, v[84:87]
	v_mfma_f32_16x16x4_f32 v[88:91], v104, v95, v[88:91]
	global_load_dwordx4 v[92:95], v108, s[50:51]
	v_add_u32_e32 v108, 0x2000, v108
	ds_read_b32 v104, v107 offset:2304
	s_waitcnt vmcnt(2) lgkmcnt(2)
	v_mfma_f32_16x16x4_f32 v[76:79], v105, v96, v[76:79]
	v_mfma_f32_16x16x4_f32 v[80:83], v105, v97, v[80:83]
	v_mfma_f32_16x16x4_f32 v[84:87], v105, v98, v[84:87]
	v_mfma_f32_16x16x4_f32 v[88:91], v105, v99, v[88:91]
	global_load_dwordx4 v[96:99], v108, s[50:51]
	v_add_u32_e32 v108, 0x2000, v108
	ds_read_b32 v105, v107 offset:2560
	s_waitcnt vmcnt(2) lgkmcnt(2)
	v_mfma_f32_16x16x4_f32 v[76:79], v106, v100, v[76:79]
	v_mfma_f32_16x16x4_f32 v[80:83], v106, v101, v[80:83]
	v_mfma_f32_16x16x4_f32 v[84:87], v106, v102, v[84:87]
	v_mfma_f32_16x16x4_f32 v[88:91], v106, v103, v[88:91]
	global_load_dwordx4 v[100:103], v108, s[50:51]
	v_add_u32_e32 v108, 0x2000, v108
	ds_read_b32 v106, v107 offset:2816
	s_waitcnt vmcnt(2) lgkmcnt(2)
	v_mfma_f32_16x16x4_f32 v[76:79], v104, v92, v[76:79]
	v_mfma_f32_16x16x4_f32 v[80:83], v104, v93, v[80:83]
	v_mfma_f32_16x16x4_f32 v[84:87], v104, v94, v[84:87]
	v_mfma_f32_16x16x4_f32 v[88:91], v104, v95, v[88:91]
	global_load_dwordx4 v[92:95], v108, s[50:51]
	v_add_u32_e32 v108, 0x2000, v108
	ds_read_b32 v104, v107 offset:3072
	s_waitcnt vmcnt(2) lgkmcnt(2)
	v_mfma_f32_16x16x4_f32 v[76:79], v105, v96, v[76:79]
	v_mfma_f32_16x16x4_f32 v[80:83], v105, v97, v[80:83]
	v_mfma_f32_16x16x4_f32 v[84:87], v105, v98, v[84:87]
	v_mfma_f32_16x16x4_f32 v[88:91], v105, v99, v[88:91]
	global_load_dwordx4 v[96:99], v108, s[50:51]
	v_add_u32_e32 v108, 0x2000, v108
	ds_read_b32 v105, v107 offset:3328
	s_waitcnt vmcnt(2) lgkmcnt(2)
	v_mfma_f32_16x16x4_f32 v[76:79], v106, v100, v[76:79]
	v_mfma_f32_16x16x4_f32 v[80:83], v106, v101, v[80:83]
	v_mfma_f32_16x16x4_f32 v[84:87], v106, v102, v[84:87]
	v_mfma_f32_16x16x4_f32 v[88:91], v106, v103, v[88:91]
	global_load_dwordx4 v[100:103], v108, s[50:51]
	v_add_u32_e32 v108, 0x2000, v108
	ds_read_b32 v106, v107 offset:3584
	s_waitcnt vmcnt(2) lgkmcnt(2)
	v_mfma_f32_16x16x4_f32 v[76:79], v104, v92, v[76:79]
	v_mfma_f32_16x16x4_f32 v[80:83], v104, v93, v[80:83]
	v_mfma_f32_16x16x4_f32 v[84:87], v104, v94, v[84:87]
	v_mfma_f32_16x16x4_f32 v[88:91], v104, v95, v[88:91]
	global_load_dwordx4 v[92:95], v108, s[50:51]
	v_add_u32_e32 v108, 0x2000, v108
	ds_read_b32 v104, v107 offset:3840
	s_waitcnt vmcnt(2) lgkmcnt(2)
	v_mfma_f32_16x16x4_f32 v[76:79], v105, v96, v[76:79]
	v_mfma_f32_16x16x4_f32 v[80:83], v105, v97, v[80:83]
	v_mfma_f32_16x16x4_f32 v[84:87], v105, v98, v[84:87]
	v_mfma_f32_16x16x4_f32 v[88:91], v105, v99, v[88:91]
	v_mov_b32_e32 v108, v111
	global_load_dwordx4 v[96:99], v108, s[52:53]
	v_add_u32_e32 v108, 0x2000, v108
	ds_read_b32 v105, v107 offset:0
	s_waitcnt vmcnt(2) lgkmcnt(2)
	v_mfma_f32_16x16x4_f32 v[76:79], v106, v100, v[76:79]
	v_mfma_f32_16x16x4_f32 v[80:83], v106, v101, v[80:83]
	v_mfma_f32_16x16x4_f32 v[84:87], v106, v102, v[84:87]
	v_mfma_f32_16x16x4_f32 v[88:91], v106, v103, v[88:91]
	global_load_dwordx4 v[100:103], v108, s[52:53]
	v_add_u32_e32 v108, 0x2000, v108
	ds_read_b32 v106, v107 offset:256
	s_waitcnt vmcnt(2) lgkmcnt(2)
	v_mfma_f32_16x16x4_f32 v[76:79], v104, v92, v[76:79]
	v_mfma_f32_16x16x4_f32 v[80:83], v104, v93, v[80:83]
	v_mfma_f32_16x16x4_f32 v[84:87], v104, v94, v[84:87]
	v_mfma_f32_16x16x4_f32 v[88:91], v104, v95, v[88:91]
	s_nop 7
	ds_write_b32 v109, v76 offset:0
	ds_write_b32 v109, v77 offset:256
	ds_write_b32 v109, v78 offset:512
	ds_write_b32 v109, v79 offset:768
	ds_write_b32 v109, v80 offset:4
	ds_write_b32 v109, v81 offset:260
	ds_write_b32 v109, v82 offset:516
	ds_write_b32 v109, v83 offset:772
	ds_write_b32 v109, v84 offset:8
	ds_write_b32 v109, v85 offset:264
	ds_write_b32 v109, v86 offset:520
	ds_write_b32 v109, v87 offset:776
	s_nop 15
	s_nop 3
	ds_write_b32 v109, v88 offset:12
	ds_write_b32 v109, v89 offset:268
	ds_write_b32 v109, v90 offset:524
	ds_write_b32 v109, v91 offset:780
	s_waitcnt lgkmcnt(0)
	global_load_dwordx4 v[92:95], v108, s[52:53]
	v_add_u32_e32 v108, 0x2000, v108
	ds_read_b32 v104, v107 offset:512
	s_waitcnt vmcnt(2) lgkmcnt(2)
	v_mfma_f32_16x16x4_f32 v[76:79], v105, v96, 0
	v_mfma_f32_16x16x4_f32 v[80:83], v105, v97, 0
	v_mfma_f32_16x16x4_f32 v[84:87], v105, v98, 0
	v_mfma_f32_16x16x4_f32 v[88:91], v105, v99, 0
	global_load_dwordx4 v[96:99], v108, s[52:53]
	v_add_u32_e32 v108, 0x2000, v108
	ds_read_b32 v105, v107 offset:768
	s_waitcnt vmcnt(2) lgkmcnt(2)
	v_mfma_f32_16x16x4_f32 v[76:79], v106, v100, v[76:79]
	v_mfma_f32_16x16x4_f32 v[80:83], v106, v101, v[80:83]
	v_mfma_f32_16x16x4_f32 v[84:87], v106, v102, v[84:87]
	v_mfma_f32_16x16x4_f32 v[88:91], v106, v103, v[88:91]
	global_load_dwordx4 v[100:103], v108, s[52:53]
	v_add_u32_e32 v108, 0x2000, v108
	ds_read_b32 v106, v107 offset:1024
	s_waitcnt vmcnt(2) lgkmcnt(2)
	v_mfma_f32_16x16x4_f32 v[76:79], v104, v92, v[76:79]
	v_mfma_f32_16x16x4_f32 v[80:83], v104, v93, v[80:83]
	v_mfma_f32_16x16x4_f32 v[84:87], v104, v94, v[84:87]
	v_mfma_f32_16x16x4_f32 v[88:91], v104, v95, v[88:91]
	global_load_dwordx4 v[92:95], v108, s[52:53]
	v_add_u32_e32 v108, 0x2000, v108
	ds_read_b32 v104, v107 offset:1280
	s_waitcnt vmcnt(2) lgkmcnt(2)
	v_mfma_f32_16x16x4_f32 v[76:79], v105, v96, v[76:79]
	v_mfma_f32_16x16x4_f32 v[80:83], v105, v97, v[80:83]
	v_mfma_f32_16x16x4_f32 v[84:87], v105, v98, v[84:87]
	v_mfma_f32_16x16x4_f32 v[88:91], v105, v99, v[88:91]
	global_load_dwordx4 v[96:99], v108, s[52:53]
	v_add_u32_e32 v108, 0x2000, v108
	ds_read_b32 v105, v107 offset:1536
	s_waitcnt vmcnt(2) lgkmcnt(2)
	v_mfma_f32_16x16x4_f32 v[76:79], v106, v100, v[76:79]
	v_mfma_f32_16x16x4_f32 v[80:83], v106, v101, v[80:83]
	v_mfma_f32_16x16x4_f32 v[84:87], v106, v102, v[84:87]
	v_mfma_f32_16x16x4_f32 v[88:91], v106, v103, v[88:91]
	global_load_dwordx4 v[100:103], v108, s[52:53]
	v_add_u32_e32 v108, 0x2000, v108
	ds_read_b32 v106, v107 offset:1792
	s_waitcnt vmcnt(2) lgkmcnt(2)
	v_mfma_f32_16x16x4_f32 v[76:79], v104, v92, v[76:79]
	v_mfma_f32_16x16x4_f32 v[80:83], v104, v93, v[80:83]
	v_mfma_f32_16x16x4_f32 v[84:87], v104, v94, v[84:87]
	v_mfma_f32_16x16x4_f32 v[88:91], v104, v95, v[88:91]
	global_load_dwordx4 v[92:95], v108, s[52:53]
	v_add_u32_e32 v108, 0x2000, v108
	ds_read_b32 v104, v107 offset:2048
	s_waitcnt vmcnt(2) lgkmcnt(2)
	v_mfma_f32_16x16x4_f32 v[76:79], v105, v96, v[76:79]
	v_mfma_f32_16x16x4_f32 v[80:83], v105, v97, v[80:83]
	v_mfma_f32_16x16x4_f32 v[84:87], v105, v98, v[84:87]
	v_mfma_f32_16x16x4_f32 v[88:91], v105, v99, v[88:91]
	global_load_dwordx4 v[96:99], v108, s[52:53]
	v_add_u32_e32 v108, 0x2000, v108
	ds_read_b32 v105, v107 offset:2304
	s_waitcnt vmcnt(2) lgkmcnt(2)
	v_mfma_f32_16x16x4_f32 v[76:79], v106, v100, v[76:79]
	v_mfma_f32_16x16x4_f32 v[80:83], v106, v101, v[80:83]
	v_mfma_f32_16x16x4_f32 v[84:87], v106, v102, v[84:87]
	v_mfma_f32_16x16x4_f32 v[88:91], v106, v103, v[88:91]
	global_load_dwordx4 v[100:103], v108, s[52:53]
	v_add_u32_e32 v108, 0x2000, v108
	ds_read_b32 v106, v107 offset:2560
	s_waitcnt vmcnt(2) lgkmcnt(2)
	v_mfma_f32_16x16x4_f32 v[76:79], v104, v92, v[76:79]
	v_mfma_f32_16x16x4_f32 v[80:83], v104, v93, v[80:83]
	v_mfma_f32_16x16x4_f32 v[84:87], v104, v94, v[84:87]
	v_mfma_f32_16x16x4_f32 v[88:91], v104, v95, v[88:91]
	global_load_dwordx4 v[92:95], v108, s[52:53]
	v_add_u32_e32 v108, 0x2000, v108
	ds_read_b32 v104, v107 offset:2816
	s_waitcnt vmcnt(2) lgkmcnt(2)
	v_mfma_f32_16x16x4_f32 v[76:79], v105, v96, v[76:79]
	v_mfma_f32_16x16x4_f32 v[80:83], v105, v97, v[80:83]
	v_mfma_f32_16x16x4_f32 v[84:87], v105, v98, v[84:87]
	v_mfma_f32_16x16x4_f32 v[88:91], v105, v99, v[88:91]
	global_load_dwordx4 v[96:99], v108, s[52:53]
	v_add_u32_e32 v108, 0x2000, v108
	ds_read_b32 v105, v107 offset:3072
	s_waitcnt vmcnt(2) lgkmcnt(2)
	v_mfma_f32_16x16x4_f32 v[76:79], v106, v100, v[76:79]
	v_mfma_f32_16x16x4_f32 v[80:83], v106, v101, v[80:83]
	v_mfma_f32_16x16x4_f32 v[84:87], v106, v102, v[84:87]
	v_mfma_f32_16x16x4_f32 v[88:91], v106, v103, v[88:91]
	global_load_dwordx4 v[100:103], v108, s[52:53]
	v_add_u32_e32 v108, 0x2000, v108
	ds_read_b32 v106, v107 offset:3328
	s_waitcnt vmcnt(2) lgkmcnt(2)
	v_mfma_f32_16x16x4_f32 v[76:79], v104, v92, v[76:79]
	v_mfma_f32_16x16x4_f32 v[80:83], v104, v93, v[80:83]
	v_mfma_f32_16x16x4_f32 v[84:87], v104, v94, v[84:87]
	v_mfma_f32_16x16x4_f32 v[88:91], v104, v95, v[88:91]
	global_load_dwordx4 v[92:95], v108, s[52:53]
	v_add_u32_e32 v108, 0x2000, v108
	ds_read_b32 v104, v107 offset:3584
	s_waitcnt vmcnt(2) lgkmcnt(2)
	v_mfma_f32_16x16x4_f32 v[76:79], v105, v96, v[76:79]
	v_mfma_f32_16x16x4_f32 v[80:83], v105, v97, v[80:83]
	v_mfma_f32_16x16x4_f32 v[84:87], v105, v98, v[84:87]
	v_mfma_f32_16x16x4_f32 v[88:91], v105, v99, v[88:91]
	global_load_dwordx4 v[96:99], v108, s[52:53]
	v_add_u32_e32 v108, 0x2000, v108
	ds_read_b32 v105, v107 offset:3840
	s_waitcnt vmcnt(2) lgkmcnt(2)
	v_mfma_f32_16x16x4_f32 v[76:79], v106, v100, v[76:79]
	v_mfma_f32_16x16x4_f32 v[80:83], v106, v101, v[80:83]
	v_mfma_f32_16x16x4_f32 v[84:87], v106, v102, v[84:87]
	v_mfma_f32_16x16x4_f32 v[88:91], v106, v103, v[88:91]
	v_mov_b32_e32 v108, v111
	global_load_dwordx4 v[100:103], v108, s[54:55]
	v_add_u32_e32 v108, 0x2000, v108
	ds_read_b32 v106, v107 offset:4096
	s_waitcnt vmcnt(2) lgkmcnt(2)
	v_mfma_f32_16x16x4_f32 v[76:79], v104, v92, v[76:79]
	v_mfma_f32_16x16x4_f32 v[80:83], v104, v93, v[80:83]
	v_mfma_f32_16x16x4_f32 v[84:87], v104, v94, v[84:87]
	v_mfma_f32_16x16x4_f32 v[88:91], v104, v95, v[88:91]
	global_load_dwordx4 v[92:95], v108, s[54:55]
	v_add_u32_e32 v108, 0x2000, v108
	ds_read_b32 v104, v107 offset:4352
	s_waitcnt vmcnt(2) lgkmcnt(2)
	v_mfma_f32_16x16x4_f32 v[76:79], v105, v96, v[76:79]
	v_mfma_f32_16x16x4_f32 v[80:83], v105, v97, v[80:83]
	v_mfma_f32_16x16x4_f32 v[84:87], v105, v98, v[84:87]
	v_mfma_f32_16x16x4_f32 v[88:91], v105, v99, v[88:91]
	s_nop 7
	ds_write_b32 v109, v76 offset:4096
	ds_write_b32 v109, v77 offset:4352
	ds_write_b32 v109, v78 offset:4608
	ds_write_b32 v109, v79 offset:4864
	ds_write_b32 v109, v80 offset:4100
	ds_write_b32 v109, v81 offset:4356
	ds_write_b32 v109, v82 offset:4612
	ds_write_b32 v109, v83 offset:4868
	ds_write_b32 v109, v84 offset:4104
	ds_write_b32 v109, v85 offset:4360
	ds_write_b32 v109, v86 offset:4616
	ds_write_b32 v109, v87 offset:4872
	s_nop 15
	s_nop 3
	ds_write_b32 v109, v88 offset:4108
	ds_write_b32 v109, v89 offset:4364
	ds_write_b32 v109, v90 offset:4620
	ds_write_b32 v109, v91 offset:4876
	s_waitcnt lgkmcnt(0)
	global_load_dwordx4 v[96:99], v108, s[54:55]
	v_add_u32_e32 v108, 0x2000, v108
	ds_read_b32 v105, v107 offset:4608
	s_waitcnt vmcnt(2) lgkmcnt(2)
	v_mfma_f32_16x16x4_f32 v[76:79], v106, v100, 0
	v_mfma_f32_16x16x4_f32 v[80:83], v106, v101, 0
	v_mfma_f32_16x16x4_f32 v[84:87], v106, v102, 0
	v_mfma_f32_16x16x4_f32 v[88:91], v106, v103, 0
	global_load_dwordx4 v[100:103], v108, s[54:55]
	v_add_u32_e32 v108, 0x2000, v108
	ds_read_b32 v106, v107 offset:4864
	s_waitcnt vmcnt(2) lgkmcnt(2)
	v_mfma_f32_16x16x4_f32 v[76:79], v104, v92, v[76:79]
	v_mfma_f32_16x16x4_f32 v[80:83], v104, v93, v[80:83]
	v_mfma_f32_16x16x4_f32 v[84:87], v104, v94, v[84:87]
	v_mfma_f32_16x16x4_f32 v[88:91], v104, v95, v[88:91]
	global_load_dwordx4 v[92:95], v108, s[54:55]
	v_add_u32_e32 v108, 0x2000, v108
	ds_read_b32 v104, v107 offset:5120
	s_waitcnt vmcnt(2) lgkmcnt(2)
	v_mfma_f32_16x16x4_f32 v[76:79], v105, v96, v[76:79]
	v_mfma_f32_16x16x4_f32 v[80:83], v105, v97, v[80:83]
	v_mfma_f32_16x16x4_f32 v[84:87], v105, v98, v[84:87]
	v_mfma_f32_16x16x4_f32 v[88:91], v105, v99, v[88:91]
	global_load_dwordx4 v[96:99], v108, s[54:55]
	v_add_u32_e32 v108, 0x2000, v108
	ds_read_b32 v105, v107 offset:5376
	s_waitcnt vmcnt(2) lgkmcnt(2)
	v_mfma_f32_16x16x4_f32 v[76:79], v106, v100, v[76:79]
	v_mfma_f32_16x16x4_f32 v[80:83], v106, v101, v[80:83]
	v_mfma_f32_16x16x4_f32 v[84:87], v106, v102, v[84:87]
	v_mfma_f32_16x16x4_f32 v[88:91], v106, v103, v[88:91]
	global_load_dwordx4 v[100:103], v108, s[54:55]
	v_add_u32_e32 v108, 0x2000, v108
	ds_read_b32 v106, v107 offset:5632
	s_waitcnt vmcnt(2) lgkmcnt(2)
	v_mfma_f32_16x16x4_f32 v[76:79], v104, v92, v[76:79]
	v_mfma_f32_16x16x4_f32 v[80:83], v104, v93, v[80:83]
	v_mfma_f32_16x16x4_f32 v[84:87], v104, v94, v[84:87]
	v_mfma_f32_16x16x4_f32 v[88:91], v104, v95, v[88:91]
	global_load_dwordx4 v[92:95], v108, s[54:55]
	v_add_u32_e32 v108, 0x2000, v108
	ds_read_b32 v104, v107 offset:5888
	s_waitcnt vmcnt(2) lgkmcnt(2)
	v_mfma_f32_16x16x4_f32 v[76:79], v105, v96, v[76:79]
	v_mfma_f32_16x16x4_f32 v[80:83], v105, v97, v[80:83]
	v_mfma_f32_16x16x4_f32 v[84:87], v105, v98, v[84:87]
	v_mfma_f32_16x16x4_f32 v[88:91], v105, v99, v[88:91]
	global_load_dwordx4 v[96:99], v108, s[54:55]
	v_add_u32_e32 v108, 0x2000, v108
	ds_read_b32 v105, v107 offset:6144
	s_waitcnt vmcnt(2) lgkmcnt(2)
	v_mfma_f32_16x16x4_f32 v[76:79], v106, v100, v[76:79]
	v_mfma_f32_16x16x4_f32 v[80:83], v106, v101, v[80:83]
	v_mfma_f32_16x16x4_f32 v[84:87], v106, v102, v[84:87]
	v_mfma_f32_16x16x4_f32 v[88:91], v106, v103, v[88:91]
	global_load_dwordx4 v[100:103], v108, s[54:55]
	v_add_u32_e32 v108, 0x2000, v108
	ds_read_b32 v106, v107 offset:6400
	s_waitcnt vmcnt(2) lgkmcnt(2)
	v_mfma_f32_16x16x4_f32 v[76:79], v104, v92, v[76:79]
	v_mfma_f32_16x16x4_f32 v[80:83], v104, v93, v[80:83]
	v_mfma_f32_16x16x4_f32 v[84:87], v104, v94, v[84:87]
	v_mfma_f32_16x16x4_f32 v[88:91], v104, v95, v[88:91]
	global_load_dwordx4 v[92:95], v108, s[54:55]
	v_add_u32_e32 v108, 0x2000, v108
	ds_read_b32 v104, v107 offset:6656
	s_waitcnt vmcnt(2) lgkmcnt(2)
	v_mfma_f32_16x16x4_f32 v[76:79], v105, v96, v[76:79]
	v_mfma_f32_16x16x4_f32 v[80:83], v105, v97, v[80:83]
	v_mfma_f32_16x16x4_f32 v[84:87], v105, v98, v[84:87]
	v_mfma_f32_16x16x4_f32 v[88:91], v105, v99, v[88:91]
	global_load_dwordx4 v[96:99], v108, s[54:55]
	v_add_u32_e32 v108, 0x2000, v108
	ds_read_b32 v105, v107 offset:6912
	s_waitcnt vmcnt(2) lgkmcnt(2)
	v_mfma_f32_16x16x4_f32 v[76:79], v106, v100, v[76:79]
	v_mfma_f32_16x16x4_f32 v[80:83], v106, v101, v[80:83]
	v_mfma_f32_16x16x4_f32 v[84:87], v106, v102, v[84:87]
	v_mfma_f32_16x16x4_f32 v[88:91], v106, v103, v[88:91]
	global_load_dwordx4 v[100:103], v108, s[54:55]
	v_add_u32_e32 v108, 0x2000, v108
	ds_read_b32 v106, v107 offset:7168
	s_waitcnt vmcnt(2) lgkmcnt(2)
	v_mfma_f32_16x16x4_f32 v[76:79], v104, v92, v[76:79]
	v_mfma_f32_16x16x4_f32 v[80:83], v104, v93, v[80:83]
	v_mfma_f32_16x16x4_f32 v[84:87], v104, v94, v[84:87]
	v_mfma_f32_16x16x4_f32 v[88:91], v104, v95, v[88:91]
	global_load_dwordx4 v[92:95], v108, s[54:55]
	v_add_u32_e32 v108, 0x2000, v108
	ds_read_b32 v104, v107 offset:7424
	s_waitcnt vmcnt(2) lgkmcnt(2)
	v_mfma_f32_16x16x4_f32 v[76:79], v105, v96, v[76:79]
	v_mfma_f32_16x16x4_f32 v[80:83], v105, v97, v[80:83]
	v_mfma_f32_16x16x4_f32 v[84:87], v105, v98, v[84:87]
	v_mfma_f32_16x16x4_f32 v[88:91], v105, v99, v[88:91]
	global_load_dwordx4 v[96:99], v108, s[54:55]
	v_add_u32_e32 v108, 0x2000, v108
	ds_read_b32 v105, v107 offset:7680
	s_waitcnt vmcnt(2) lgkmcnt(2)
	v_mfma_f32_16x16x4_f32 v[76:79], v106, v100, v[76:79]
	v_mfma_f32_16x16x4_f32 v[80:83], v106, v101, v[80:83]
	v_mfma_f32_16x16x4_f32 v[84:87], v106, v102, v[84:87]
	v_mfma_f32_16x16x4_f32 v[88:91], v106, v103, v[88:91]
	global_load_dwordx4 v[100:103], v108, s[54:55]
	v_add_u32_e32 v108, 0x2000, v108
	ds_read_b32 v106, v107 offset:7936
	s_waitcnt vmcnt(2) lgkmcnt(2)
	v_mfma_f32_16x16x4_f32 v[76:79], v104, v92, v[76:79]
	v_mfma_f32_16x16x4_f32 v[80:83], v104, v93, v[80:83]
	v_mfma_f32_16x16x4_f32 v[84:87], v104, v94, v[84:87]
	v_mfma_f32_16x16x4_f32 v[88:91], v104, v95, v[88:91]
	s_waitcnt vmcnt(1) lgkmcnt(1)
	v_mfma_f32_16x16x4_f32 v[76:79], v105, v96, v[76:79]
	v_mfma_f32_16x16x4_f32 v[80:83], v105, v97, v[80:83]
	v_mfma_f32_16x16x4_f32 v[84:87], v105, v98, v[84:87]
	v_mfma_f32_16x16x4_f32 v[88:91], v105, v99, v[88:91]
	s_waitcnt vmcnt(0) lgkmcnt(0)
	v_mfma_f32_16x16x4_f32 v[76:79], v106, v100, v[76:79]
	v_mfma_f32_16x16x4_f32 v[80:83], v106, v101, v[80:83]
	v_mfma_f32_16x16x4_f32 v[84:87], v106, v102, v[84:87]
	v_mfma_f32_16x16x4_f32 v[88:91], v106, v103, v[88:91]
	s_nop 7
	ds_write_b32 v109, v76 offset:8192
	ds_write_b32 v109, v77 offset:8448
	ds_write_b32 v109, v78 offset:8704
	ds_write_b32 v109, v79 offset:8960
	ds_write_b32 v109, v80 offset:8196
	ds_write_b32 v109, v81 offset:8452
	ds_write_b32 v109, v82 offset:8708
	ds_write_b32 v109, v83 offset:8964
	ds_write_b32 v109, v84 offset:8200
	ds_write_b32 v109, v85 offset:8456
	ds_write_b32 v109, v86 offset:8712
	ds_write_b32 v109, v87 offset:8968
	s_nop 15
	s_nop 3
	ds_write_b32 v109, v88 offset:8204
	ds_write_b32 v109, v89 offset:8460
	ds_write_b32 v109, v90 offset:8716
	ds_write_b32 v109, v91 offset:8972
	s_waitcnt lgkmcnt(0)
	ds_read2st64_b32 v[62:63], v110 offset0:0 offset1:1
	ds_read2st64_b32 v[56:57], v110 offset0:2 offset1:3
	ds_read2st64_b32 v[50:51], v110 offset0:4 offset1:5
	ds_read2st64_b32 v[44:45], v110 offset0:6 offset1:7
	ds_read2st64_b32 v[38:39], v110 offset0:8 offset1:9
	ds_read2st64_b32 v[32:33], v110 offset0:10 offset1:11
	ds_read2st64_b32 v[26:27], v110 offset0:12 offset1:13
	ds_read2st64_b32 v[20:21], v110 offset0:14 offset1:15
	ds_read2st64_b32 v[64:65], v110 offset0:16 offset1:17
	ds_read2st64_b32 v[58:59], v110 offset0:18 offset1:19
	ds_read2st64_b32 v[52:53], v110 offset0:20 offset1:21
	ds_read2st64_b32 v[46:47], v110 offset0:22 offset1:23
	s_waitcnt lgkmcnt(0)
	ds_read2st64_b32 v[40:41], v110 offset0:24 offset1:25
	ds_read2st64_b32 v[34:35], v110 offset0:26 offset1:27
	ds_read2st64_b32 v[28:29], v110 offset0:28 offset1:29
	ds_read2st64_b32 v[22:23], v110 offset0:30 offset1:31
	ds_read2st64_b32 v[66:67], v110 offset0:32 offset1:33
	ds_read2st64_b32 v[60:61], v110 offset0:34 offset1:35
	ds_read2st64_b32 v[54:55], v110 offset0:36 offset1:37
	ds_read2st64_b32 v[48:49], v110 offset0:38 offset1:39
	ds_read2st64_b32 v[42:43], v110 offset0:40 offset1:41
	ds_read2st64_b32 v[36:37], v110 offset0:42 offset1:43
	ds_read2st64_b32 v[30:31], v110 offset0:44 offset1:45
	ds_read2st64_b32 v[24:25], v110 offset0:46 offset1:47
	s_waitcnt lgkmcnt(0)
	s_waitcnt lgkmcnt(0)
	s_ashr_i32 s19, s18, 31
	s_lshl_b64 s[0:1], s[18:19], 10
	v_lshlrev_b32_e32 v78, 1, v164
	v_or_b32_e32 v74, s0, v78
	v_mov_b32_e32 v75, s1
	s_or_b32 s0, s18, 1
	v_cvt_pk_bf16_f32 v17, v62, v1
	v_lshl_add_u64 v[76:77], s[12:13], 0, v[74:75]
	s_ashr_i32 s1, s0, 31
	global_store_short v[76:77], v17, off
	v_cvt_pk_bf16_f32 v17, v64, v1
	v_lshl_add_u64 v[76:77], s[14:15], 0, v[74:75]
	v_lshl_add_u64 v[74:75], s[92:93], 0, v[74:75]
	s_lshl_b64 s[0:1], s[0:1], 9
	global_store_short v[76:77], v17, off
	v_cvt_pk_bf16_f32 v17, v66, v1
	global_store_short v[74:75], v17, off
	v_lshl_add_u64 v[74:75], s[0:1], 0, v[164:165]
	v_cvt_pk_bf16_f32 v17, v63, v1
	v_lshlrev_b64 v[62:63], 1, v[74:75]
	s_or_b32 s0, s18, 2
	v_lshl_add_u64 v[74:75], s[12:13], 0, v[62:63]
	s_ashr_i32 s1, s0, 31
	global_store_short v[74:75], v17, off
	v_cvt_pk_bf16_f32 v17, v65, v1
	v_lshl_add_u64 v[64:65], s[14:15], 0, v[62:63]
	v_lshl_add_u64 v[62:63], s[92:93], 0, v[62:63]
	s_lshl_b64 s[0:1], s[0:1], 10
	global_store_short v[64:65], v17, off
	v_cvt_pk_bf16_f32 v17, v67, v1
	global_store_short v[62:63], v17, off
	v_or_b32_e32 v62, s0, v78
	v_mov_b32_e32 v63, s1
	s_or_b32 s0, s18, 3
	v_cvt_pk_bf16_f32 v17, v56, v1
	v_lshl_add_u64 v[64:65], s[12:13], 0, v[62:63]
	s_ashr_i32 s1, s0, 31
	global_store_short v[64:65], v17, off
	v_cvt_pk_bf16_f32 v17, v58, v1
	v_lshl_add_u64 v[64:65], s[14:15], 0, v[62:63]
	v_lshl_add_u64 v[62:63], s[92:93], 0, v[62:63]
	s_lshl_b64 s[0:1], s[0:1], 9
	global_store_short v[64:65], v17, off
	v_cvt_pk_bf16_f32 v17, v60, v1
	global_store_short v[62:63], v17, off
	v_lshl_add_u64 v[62:63], s[0:1], 0, v[164:165]
	v_cvt_pk_bf16_f32 v17, v57, v1
	v_lshlrev_b64 v[56:57], 1, v[62:63]
	s_or_b32 s0, s18, 4
	v_lshl_add_u64 v[62:63], s[12:13], 0, v[56:57]
	s_ashr_i32 s1, s0, 31
	global_store_short v[62:63], v17, off
	v_cvt_pk_bf16_f32 v17, v59, v1
	v_lshl_add_u64 v[58:59], s[14:15], 0, v[56:57]
	v_lshl_add_u64 v[56:57], s[92:93], 0, v[56:57]
	s_lshl_b64 s[0:1], s[0:1], 10
	global_store_short v[58:59], v17, off
	v_cvt_pk_bf16_f32 v17, v61, v1
	global_store_short v[56:57], v17, off
	v_or_b32_e32 v56, s0, v78
	v_mov_b32_e32 v57, s1
	s_or_b32 s0, s18, 5
	v_cvt_pk_bf16_f32 v17, v50, v1
	v_lshl_add_u64 v[58:59], s[12:13], 0, v[56:57]
	s_ashr_i32 s1, s0, 31
	global_store_short v[58:59], v17, off
	v_cvt_pk_bf16_f32 v17, v52, v1
	v_lshl_add_u64 v[58:59], s[14:15], 0, v[56:57]
	v_lshl_add_u64 v[56:57], s[92:93], 0, v[56:57]
	s_lshl_b64 s[0:1], s[0:1], 9
	global_store_short v[58:59], v17, off
	v_cvt_pk_bf16_f32 v17, v54, v1
	global_store_short v[56:57], v17, off
	v_lshl_add_u64 v[56:57], s[0:1], 0, v[164:165]
	v_cvt_pk_bf16_f32 v17, v51, v1
	v_lshlrev_b64 v[50:51], 1, v[56:57]
	s_or_b32 s0, s18, 6
	v_lshl_add_u64 v[56:57], s[12:13], 0, v[50:51]
	s_ashr_i32 s1, s0, 31
	global_store_short v[56:57], v17, off
	v_cvt_pk_bf16_f32 v17, v53, v1
	v_lshl_add_u64 v[52:53], s[14:15], 0, v[50:51]
	v_lshl_add_u64 v[50:51], s[92:93], 0, v[50:51]
	s_lshl_b64 s[0:1], s[0:1], 10
	global_store_short v[52:53], v17, off
	v_cvt_pk_bf16_f32 v17, v55, v1
	global_store_short v[50:51], v17, off
	v_or_b32_e32 v50, s0, v78
	v_mov_b32_e32 v51, s1
	s_or_b32 s0, s18, 7
	v_cvt_pk_bf16_f32 v17, v44, v1
	v_lshl_add_u64 v[52:53], s[12:13], 0, v[50:51]
	s_ashr_i32 s1, s0, 31
	global_store_short v[52:53], v17, off
	v_cvt_pk_bf16_f32 v17, v46, v1
	v_lshl_add_u64 v[52:53], s[14:15], 0, v[50:51]
	v_lshl_add_u64 v[50:51], s[92:93], 0, v[50:51]
	s_lshl_b64 s[0:1], s[0:1], 9
	global_store_short v[52:53], v17, off
	v_cvt_pk_bf16_f32 v17, v48, v1
	global_store_short v[50:51], v17, off
	v_lshl_add_u64 v[50:51], s[0:1], 0, v[164:165]
	v_cvt_pk_bf16_f32 v17, v45, v1
	v_lshlrev_b64 v[44:45], 1, v[50:51]
	s_or_b32 s0, s18, 8
	v_lshl_add_u64 v[50:51], s[12:13], 0, v[44:45]
	s_ashr_i32 s1, s0, 31
	global_store_short v[50:51], v17, off
	v_cvt_pk_bf16_f32 v17, v47, v1
	v_lshl_add_u64 v[46:47], s[14:15], 0, v[44:45]
	v_lshl_add_u64 v[44:45], s[92:93], 0, v[44:45]
	s_lshl_b64 s[0:1], s[0:1], 10
	global_store_short v[46:47], v17, off
	v_cvt_pk_bf16_f32 v17, v49, v1
	global_store_short v[44:45], v17, off
	v_or_b32_e32 v44, s0, v78
	v_mov_b32_e32 v45, s1
	s_or_b32 s0, s18, 9
	v_cvt_pk_bf16_f32 v17, v38, v1
	v_lshl_add_u64 v[46:47], s[12:13], 0, v[44:45]
	s_ashr_i32 s1, s0, 31
	global_store_short v[46:47], v17, off
	v_cvt_pk_bf16_f32 v17, v40, v1
	v_lshl_add_u64 v[46:47], s[14:15], 0, v[44:45]
	v_lshl_add_u64 v[44:45], s[92:93], 0, v[44:45]
	s_lshl_b64 s[0:1], s[0:1], 9
	global_store_short v[46:47], v17, off
	v_cvt_pk_bf16_f32 v17, v42, v1
	global_store_short v[44:45], v17, off
	v_lshl_add_u64 v[44:45], s[0:1], 0, v[164:165]
	v_cvt_pk_bf16_f32 v17, v39, v1
	v_lshlrev_b64 v[38:39], 1, v[44:45]
	s_or_b32 s0, s18, 10
	v_lshl_add_u64 v[44:45], s[12:13], 0, v[38:39]
	s_ashr_i32 s1, s0, 31
	global_store_short v[44:45], v17, off
	v_cvt_pk_bf16_f32 v17, v41, v1
	v_lshl_add_u64 v[40:41], s[14:15], 0, v[38:39]
	v_lshl_add_u64 v[38:39], s[92:93], 0, v[38:39]
	s_lshl_b64 s[0:1], s[0:1], 10
	global_store_short v[40:41], v17, off
	v_cvt_pk_bf16_f32 v17, v43, v1
	global_store_short v[38:39], v17, off
	v_or_b32_e32 v38, s0, v78
	v_mov_b32_e32 v39, s1
	s_or_b32 s0, s18, 11
	v_cvt_pk_bf16_f32 v17, v32, v1
	v_lshl_add_u64 v[40:41], s[12:13], 0, v[38:39]
	s_ashr_i32 s1, s0, 31
	global_store_short v[40:41], v17, off
	v_cvt_pk_bf16_f32 v17, v34, v1
	v_lshl_add_u64 v[40:41], s[14:15], 0, v[38:39]
	v_lshl_add_u64 v[38:39], s[92:93], 0, v[38:39]
	s_lshl_b64 s[0:1], s[0:1], 9
	global_store_short v[40:41], v17, off
	v_cvt_pk_bf16_f32 v17, v36, v1
	global_store_short v[38:39], v17, off
	v_lshl_add_u64 v[38:39], s[0:1], 0, v[164:165]
	v_cvt_pk_bf16_f32 v17, v33, v1
	v_lshlrev_b64 v[32:33], 1, v[38:39]
	s_or_b32 s0, s18, 12
	v_lshl_add_u64 v[38:39], s[12:13], 0, v[32:33]
	s_ashr_i32 s1, s0, 31
	global_store_short v[38:39], v17, off
	v_cvt_pk_bf16_f32 v17, v35, v1
	v_lshl_add_u64 v[34:35], s[14:15], 0, v[32:33]
	v_lshl_add_u64 v[32:33], s[92:93], 0, v[32:33]
	s_lshl_b64 s[0:1], s[0:1], 10
	global_store_short v[34:35], v17, off
	v_cvt_pk_bf16_f32 v17, v37, v1
	global_store_short v[32:33], v17, off
	v_or_b32_e32 v32, s0, v78
	v_mov_b32_e32 v33, s1
	s_or_b32 s0, s18, 13
	v_cvt_pk_bf16_f32 v17, v26, v1
	v_lshl_add_u64 v[34:35], s[12:13], 0, v[32:33]
	s_ashr_i32 s1, s0, 31
	global_store_short v[34:35], v17, off
	v_cvt_pk_bf16_f32 v17, v28, v1
	v_lshl_add_u64 v[34:35], s[14:15], 0, v[32:33]
	v_lshl_add_u64 v[32:33], s[92:93], 0, v[32:33]
	s_lshl_b64 s[0:1], s[0:1], 9
	global_store_short v[34:35], v17, off
	v_cvt_pk_bf16_f32 v17, v30, v1
	global_store_short v[32:33], v17, off
	v_lshl_add_u64 v[32:33], s[0:1], 0, v[164:165]
	v_cvt_pk_bf16_f32 v17, v27, v1
	v_lshlrev_b64 v[26:27], 1, v[32:33]
	s_or_b32 s0, s18, 14
	v_lshl_add_u64 v[32:33], s[12:13], 0, v[26:27]
	s_ashr_i32 s1, s0, 31
	global_store_short v[32:33], v17, off
	v_cvt_pk_bf16_f32 v17, v29, v1
	v_lshl_add_u64 v[28:29], s[14:15], 0, v[26:27]
	v_lshl_add_u64 v[26:27], s[92:93], 0, v[26:27]
	s_lshl_b64 s[0:1], s[0:1], 10
	global_store_short v[28:29], v17, off
	v_cvt_pk_bf16_f32 v17, v31, v1
	global_store_short v[26:27], v17, off
	v_or_b32_e32 v26, s0, v78
	v_mov_b32_e32 v27, s1
	s_or_b32 s0, s18, 15
	v_cvt_pk_bf16_f32 v17, v20, v1
	v_lshl_add_u64 v[28:29], s[12:13], 0, v[26:27]
	s_ashr_i32 s1, s0, 31
	global_store_short v[28:29], v17, off
	v_cvt_pk_bf16_f32 v17, v22, v1
	v_lshl_add_u64 v[28:29], s[14:15], 0, v[26:27]
	v_lshl_add_u64 v[26:27], s[92:93], 0, v[26:27]
	s_lshl_b64 s[0:1], s[0:1], 9
	global_store_short v[28:29], v17, off
	v_cvt_pk_bf16_f32 v17, v24, v1
	global_store_short v[26:27], v17, off
	v_lshl_add_u64 v[26:27], s[0:1], 0, v[164:165]
	v_cvt_pk_bf16_f32 v17, v21, v1
	v_lshlrev_b64 v[20:21], 1, v[26:27]
	v_lshl_add_u64 v[26:27], s[12:13], 0, v[20:21]
	s_add_i32 s48, s48, s30
	global_store_short v[26:27], v17, off
	v_cvt_pk_bf16_f32 v17, v23, v1
	v_lshl_add_u64 v[22:23], s[14:15], 0, v[20:21]
	v_lshl_add_u64 v[20:21], s[92:93], 0, v[20:21]
	s_cmpk_gt_i32 s48, 0x3ff
	global_store_short v[22:23], v17, off
	v_cvt_pk_bf16_f32 v17, v25, v1
	global_store_short v[20:21], v17, off
	s_barrier
	s_cbranch_scc0 .LBB0_944
